# row-norm rebalance (P7,P11) + P7 next-row prefetch that follows the rebalanced row list
# baseline (speedup 1.0000x reference)
.LBB0_1005:
	v_readlane_b32 s2, v248, 0
	v_readlane_b32 s3, v248, 1
	s_cmp_lt_i32 s2, 8
	s_cselect_b64 s[2:3], -1, 0
	s_and_b64 s[2:3], s[2:3], s[0:1]
	s_andn2_b64 vcc, exec, s[2:3]
	s_cbranch_vccnz .LBB0_1019
	v_lshl_or_b32 v34, s82, 3, v210
	s_movk_i32 s0, 0x4080
	v_cmp_gt_i32_e32 vcc, s0, v34
	s_and_saveexec_b64 s[4:5], vcc
	s_cbranch_execz .LBB0_1018
	v_lshlrev_b32_e32 v1, 2, v0
	v_and_b32_e32 v18, 0xfc, v1
	v_lshlrev_b32_e32 v36, 2, v18
	v_mbcnt_lo_u32_b32 v1, -1, 0
	v_mbcnt_hi_u32_b32 v19, -1, v1
	v_and_b32_e32 v22, 64, v19
	v_xor_b32_e32 v1, 1, v19
	v_add_u32_e32 v22, 64, v22
	v_cmp_lt_i32_e32 vcc, v1, v22
	v_xor_b32_e32 v23, 2, v19
	v_readlane_b32 s8, v248, 2
	v_cndmask_b32_e32 v1, v19, v1, vcc
	v_cmp_lt_i32_e32 vcc, v23, v22
	v_mov_b32_e32 v37, 0
	v_readlane_b32 s9, v248, 3
	v_cndmask_b32_e32 v23, v19, v23, vcc
	v_lshlrev_b32_e32 v46, 2, v23
	v_xor_b32_e32 v23, 4, v19
	v_cmp_lt_i32_e32 vcc, v23, v22
	v_readlane_b32 s10, v248, 4
	v_readlane_b32 s11, v248, 5
	v_cndmask_b32_e32 v23, v19, v23, vcc
	v_lshlrev_b32_e32 v47, 2, v23
	v_xor_b32_e32 v23, 8, v19
	v_cmp_lt_i32_e32 vcc, v23, v22
	s_cmp_lg_u64 s[10:11], 0
	v_lshl_add_u64 v[20:21], s[94:95], 0, v[36:37]
	v_cndmask_b32_e32 v23, v19, v23, vcc
	v_lshlrev_b32_e32 v48, 2, v23
	v_xor_b32_e32 v23, 16, v19
	v_cmp_lt_i32_e32 vcc, v23, v22
	s_mov_b64 s[8:9], 0xb3d6400
	v_lshl_add_u64 v[40:41], s[92:93], 0, v[36:37]
	v_cndmask_b32_e32 v23, v19, v23, vcc
	v_lshlrev_b32_e32 v49, 2, v23
	v_xor_b32_e32 v23, 32, v19
	v_lshlrev_b32_e32 v36, 1, v18
	v_cmp_lt_i32_e32 vcc, v23, v22
	s_cselect_b64 s[0:1], -1, 0
	v_lshl_add_u64 v[38:39], v[20:21], 0, s[8:9]
	v_lshl_add_u64 v[20:21], s[94:95], 0, v[36:37]
	s_mov_b64 s[8:9], 0xbf0cc00
	v_cndmask_b32_e32 v19, v19, v23, vcc
	v_readlane_b32 s12, v248, 6
	v_readlane_b32 s13, v248, 7
	v_readlane_b32 s14, v248, 8
	v_readlane_b32 s15, v248, 9
	v_readlane_b32 s16, v248, 10
	v_readlane_b32 s17, v248, 11
	v_readlane_b32 s18, v248, 12
	v_readlane_b32 s19, v248, 13
	v_readlane_b32 s20, v248, 14
	v_readlane_b32 s21, v248, 15
	v_readlane_b32 s22, v248, 16
	v_lshl_add_u64 v[42:43], v[20:21], 0, s[8:9]
	v_lshlrev_b32_e32 v50, 2, v19
	s_mov_b64 s[8:9], 0x1f80000
	v_cndmask_b32_e64 v19, 0, 1, s[0:1]
	s_mov_b64 s[6:7], 0
	v_lshlrev_b32_e32 v1, 2, v1
	v_lshl_add_u64 v[44:45], v[20:21], 0, s[8:9]
	s_waitcnt lgkmcnt(0)
	s_lshl_b32 s12, s96, 3
	s_movk_i32 s13, 0x3fff
	v_cmp_ne_u32_e64 s[0:1], 1, v19
	v_lshlrev_b32_e32 v36, 2, v18
	s_mov_b32 s14, 0x80000
	s_mov_b32 s15, 0x100000
	s_mov_b32 s16, 0x180000
	s_mov_b32 s17, 0x200000
	s_mov_b32 s18, 0x280000
	s_mov_b32 s19, 0x300000
	s_mov_b32 s20, 0x380000
	v_mov_b32_e32 v51, 0x3727c5ac
	s_mov_b32 s21, 0x800000
	s_movk_i32 s22, 0x407f
	v_readlane_b32 s23, v248, 17
	v_add_u32_e32 v228, 0xffffff80, v34
	v_and_b32_e32 v229, 0x7f, v228
	v_lshrrev_b32_e32 v230, 7, v228
	v_lshl_add_u32 v229, v230, 11, v229
	v_add_u32_e32 v229, 0x3000, v229
	v_mov_b32_e32 v224, -1
	v_mov_b32_e32 v226, -1
	v_mov_b32_e32 v227, 0x7fffffff
	v_mov_b32_e32 v225, v229
	v_add_u32_e32 v230, 0x4000, v34
	v_add_u32_e32 v231, 0x800, v229
	v_cmp_gt_u32_e32 vcc, 0x100, v228
	s_nop 1
	v_cndmask_b32_e32 v224, v224, v230, vcc
	v_cndmask_b32_e32 v226, v226, v231, vcc
	v_add_u32_e32 v231, 0x3000, v34
	v_cmp_gt_u32_e32 vcc, 0x80, v34
	s_nop 1
	v_cndmask_b32_e32 v224, v224, v231, vcc
	v_cndmask_b32_e32 v225, v225, v230, vcc
	v_mov_b32_e32 v222, v34
	v_mov_b32_e32 v223, 0
	v_lshlrev_b64 v[220:221], 11, v[222:223]
	v_lshl_add_u64 v[220:221], v[42:43], 0, v[220:221]
	global_load_dwordx2 v[212:213], v[220:221], off
	global_load_dwordx2 v[214:215], v[220:221], off offset:512
	global_load_dwordx2 v[216:217], v[220:221], off offset:1024
	global_load_dwordx2 v[218:219], v[220:221], off offset:1536
	global_load_dwordx4 v[2:5], v36, s[80:81]
	global_load_dwordx4 v[6:9], v36, s[80:81] offset:1024
	global_load_dwordx4 v[10:13], v36, s[80:81] offset:2048
	global_load_dwordx4 v[14:17], v36, s[80:81] offset:3072
	s_branch .LBB0_1009
.LBB0_1008:
	s_or_b64 exec, exec, s[8:9]
	v_pk_mul_f32 v[64:65], v[30:31], v[30:31]
	v_pk_mul_f32 v[66:67], v[26:27], v[26:27]
	v_pk_mul_f32 v[60:61], v[32:33], v[32:33]
	v_pk_mul_f32 v[62:63], v[28:29], v[28:29]
	v_mov_b32_e32 v68, v64
	v_mov_b32_e32 v69, v66
	v_mov_b32_e32 v66, v65
	v_pk_add_f32 v[64:65], v[68:69], v[66:67]
	v_mov_b32_e32 v66, v60
	v_mov_b32_e32 v67, v62
	v_pk_mul_f32 v[56:57], v[18:19], v[18:19]
	v_pk_mul_f32 v[58:59], v[22:23], v[22:23]
	v_pk_add_f32 v[64:65], v[66:67], v[64:65]
	v_mov_b32_e32 v62, v61
	v_pk_mul_f32 v[52:53], v[20:21], v[20:21]
	v_pk_mul_f32 v[54:55], v[24:25], v[24:25]
	v_pk_add_f32 v[60:61], v[62:63], v[64:65]
	v_mov_b32_e32 v62, v56
	v_mov_b32_e32 v63, v58
	v_mov_b32_e32 v58, v57
	v_pk_add_f32 v[56:57], v[62:63], v[58:59]
	v_mov_b32_e32 v58, v52
	v_mov_b32_e32 v59, v54
	v_pk_add_f32 v[56:57], v[58:59], v[56:57]
	v_mov_b32_e32 v54, v53
	v_pk_add_f32 v[52:53], v[54:55], v[56:57]
	v_add_f32_e32 v54, v60, v61
	v_add_f32_e32 v53, v53, v54
	v_add_f32_e32 v52, v52, v53
	ds_bpermute_b32 v53, v1, v52
	s_waitcnt lgkmcnt(0)
	v_add_f32_e32 v52, v52, v53
	ds_bpermute_b32 v53, v46, v52
	s_waitcnt lgkmcnt(0)
	v_add_f32_e32 v52, v52, v53
	ds_bpermute_b32 v53, v47, v52
	s_waitcnt lgkmcnt(0)
	v_add_f32_e32 v52, v52, v53
	ds_bpermute_b32 v53, v48, v52
	s_waitcnt lgkmcnt(0)
	v_add_f32_e32 v52, v52, v53
	ds_bpermute_b32 v53, v49, v52
	s_waitcnt lgkmcnt(0)
	v_add_f32_e32 v52, v52, v53
	ds_bpermute_b32 v53, v50, v52
	s_waitcnt lgkmcnt(0)
	v_add_f32_e32 v52, v52, v53
	v_fmamk_f32 v52, v52, 0x3a800000, v51
	v_mul_f32_e32 v53, 0x4b800000, v52
	v_cmp_gt_f32_e32 vcc, s21, v52
	s_nop 1
	v_cndmask_b32_e32 v52, v52, v53, vcc
	v_rsq_f32_e32 v54, v52
	v_lshlrev_b64 v[52:53], 11, v[34:35]
	v_add_u32_e32 v34, s12, v34
	v_lshl_add_u64 v[52:53], v[44:45], 0, v[52:53]
	v_mul_f32_e32 v35, 0x45800000, v54
	v_cndmask_b32_e32 v54, v54, v35, vcc
	v_pk_mul_f32 v[30:31], v[30:31], v[54:55] op_sel_hi:[1,0]
	v_pk_mul_f32 v[32:33], v[32:33], v[54:55] op_sel_hi:[1,0]
	v_pk_mul_f32 v[26:27], v[26:27], v[54:55] op_sel_hi:[1,0]
	v_pk_mul_f32 v[28:29], v[28:29], v[54:55] op_sel_hi:[1,0]
	v_pk_mul_f32 v[22:23], v[22:23], v[54:55] op_sel_hi:[1,0]
	v_pk_mul_f32 v[24:25], v[24:25], v[54:55] op_sel_hi:[1,0]
	v_pk_mul_f32 v[18:19], v[18:19], v[54:55] op_sel_hi:[1,0]
	v_pk_mul_f32 v[20:21], v[20:21], v[54:55] op_sel_hi:[1,0]
	s_waitcnt vmcnt(4)
	v_pk_mul_f32 v[32:33], v[4:5], v[32:33]
	v_pk_mul_f32 v[30:31], v[2:3], v[30:31]
	v_pk_mul_f32 v[28:29], v[8:9], v[28:29]
	v_pk_mul_f32 v[26:27], v[6:7], v[26:27]
	v_pk_mul_f32 v[24:25], v[12:13], v[24:25]
	v_pk_mul_f32 v[22:23], v[10:11], v[22:23]
	v_pk_mul_f32 v[20:21], v[16:17], v[20:21]
	v_pk_mul_f32 v[18:19], v[14:15], v[18:19]
	v_cmp_eq_u32_e32 vcc, v34, v224
	s_nop 1
	v_cndmask_b32_e32 v34, v34, v225, vcc
	v_cmp_eq_u32_e32 vcc, v34, v226
	s_nop 1
	v_cndmask_b32_e32 v34, v34, v227, vcc
	v_cmp_lt_i32_e32 vcc, s22, v34
	v_cvt_pk_bf16_f32 v30, v30, v31
	v_cvt_pk_bf16_f32 v31, v32, v33
	v_cvt_pk_bf16_f32 v26, v26, v27
	v_cvt_pk_bf16_f32 v27, v28, v29
	v_cvt_pk_bf16_f32 v22, v22, v23
	v_cvt_pk_bf16_f32 v23, v24, v25
	v_cvt_pk_bf16_f32 v18, v18, v19
	v_cvt_pk_bf16_f32 v19, v20, v21
	s_or_b64 s[6:7], vcc, s[6:7]
	global_store_dwordx2 v[52:53], v[30:31], off
	global_store_dwordx2 v[52:53], v[26:27], off offset:512
	global_store_dwordx2 v[52:53], v[22:23], off offset:1024
	global_store_dwordx2 v[52:53], v[18:19], off offset:1536
	s_andn2_b64 exec, exec, s[6:7]
	s_cbranch_execz .LBB0_1018

.LBB0_1015:
	s_or_saveexec_b64 s[8:9], s[8:9]
	v_ashrrev_i32_e32 v35, 31, v34
	s_xor_b64 exec, exec, s[8:9]
	s_cbranch_execz .LBB0_1008
	s_waitcnt vmcnt(4)
	v_lshlrev_b32_e32 v30, 16, v212
	v_and_b32_e32 v31, 0xffff0000, v212
	v_lshlrev_b32_e32 v32, 16, v213
	v_and_b32_e32 v33, 0xffff0000, v213
	v_lshlrev_b32_e32 v26, 16, v214
	v_and_b32_e32 v27, 0xffff0000, v214
	v_lshlrev_b32_e32 v28, 16, v215
	v_and_b32_e32 v29, 0xffff0000, v215
	v_lshlrev_b32_e32 v22, 16, v216
	v_and_b32_e32 v23, 0xffff0000, v216
	v_lshlrev_b32_e32 v24, 16, v217
	v_and_b32_e32 v25, 0xffff0000, v217
	v_lshlrev_b32_e32 v18, 16, v218
	v_and_b32_e32 v19, 0xffff0000, v218
	v_lshlrev_b32_e32 v20, 16, v219
	v_and_b32_e32 v21, 0xffff0000, v219
	v_add_u32_e32 v222, s12, v34
	v_cmp_eq_u32_e32 vcc, v222, v224
	s_nop 1
	v_cndmask_b32_e32 v222, v222, v225, vcc
	v_cmp_eq_u32_e32 vcc, v222, v226
	s_nop 1
	v_cndmask_b32_e32 v222, v222, v227, vcc
	v_cmp_ge_i32_e32 vcc, s13, v222
	s_and_saveexec_b64 s[98:99], vcc
	s_cbranch_execz .Lp7_nopf
	v_mov_b32_e32 v223, 0
	v_lshlrev_b64 v[220:221], 11, v[222:223]
	v_lshl_add_u64 v[220:221], v[42:43], 0, v[220:221]
	global_load_dwordx2 v[212:213], v[220:221], off
	global_load_dwordx2 v[214:215], v[220:221], off offset:512
	global_load_dwordx2 v[216:217], v[220:221], off offset:1024
	global_load_dwordx2 v[218:219], v[220:221], off offset:1536
.Lp7_nopf:
	s_mov_b64 exec, s[98:99]
	s_branch .LBB0_1008
